# plus split-K over the two virtual blocks for the three 64x64-tile sample-row GEMMs (one tile per workgroup on all 256 workgroups)
# speedup vs baseline: 1.0666x; 1.0121x over previous
; #define VLOOP(t, N) for (int t##0_ = 2 * bid, t = min(t##0_ + vb, (N) - 1); t##0_ < (N); t##0_ += VG, t = min(t##0_ + vb, (N) - 1))
; template <int WT, class Epi>
; DEV void gemm_tile(const bf16_t* __restrict__ A, int lda, const bf16_t* __restrict__ Bt, int ldb, int K, unsigned char* lds, const Epi& epi) {
;     ...
;         nxt = cur; cur += STB; if (cur == NSTG * STB) cur = 0;
;     }
;     ...
;     __syncthreads();
; __global__ void __launch_bounds__(512) hymba_fwd(Params p) {
;     ...
;         VLOOP(t, 8 * 32) { const int mt = t & 7, nt = t >> 3;
;             EpiResidBS e{x1 + (size_t)(TP + mt * 64) * LDB + nt * 64, x2 + (size_t)(TP + mt * 64) * LDB + nt * 64, LDB};
;             gemm_tile<32>(ctx + (size_t)(TP + mt * 64) * LDB, LDB, Wt_co + (size_t)nt * 64 * LDB, LDB, D, vlds, e);
.LBB0_1007:
	s_movk_i32 s96, 0x7f
	s_cmpk_eq_i32 s33, 0x100
	s_cselect_b32 s96, 0xff, s96
	s_cmp_gt_i32 s2, s96
	s_cbranch_scc1 .LBB0_1024
	s_ashr_i32 s44, s20, 8
	s_lshl_b32 s46, s2, 1
	s_add_i32 s4, s44, s46
	s_min_i32 s6, s4, 0xff
	s_mov_b32 s96, 32
	s_mov_b32 s97, 29
	s_mov_b32 s98, 28
	s_mov_b32 s99, 0
	s_cmpk_lg_i32 s33, 0x100
	s_cbranch_scc1 .Lsk5_hdr
	s_mov_b32 s6, s2
	s_mov_b32 s96, 16
	s_mov_b32 s97, 13
	s_mov_b32 s98, 12
	s_lshl_b32 s99, s44, 11
.Lsk5_hdr:
	s_load_dwordx2 s[4:5], s[0:1], 0x8
	s_lshl_b32 s45, s44, 16
	v_and_b32_e32 v1, 0xff, v0
	s_or_b32 s47, s45, 0x4000
	s_or_b32 s48, s45, 0x8000
	s_mov_b32 s7, 0
	v_mov_b32_e32 v24, 0x42000
	s_movk_i32 s49, 0x1080
	v_mov_b32_e32 v19, 0
	s_mov_b64 s[8:9], 0x21000
	s_mov_b64 s[10:11], 0x80
	s_mov_b64 s[12:13], 0x21080
	s_mov_b64 s[16:17], 0x100
	s_mov_b64 s[18:19], 0x21100
	s_mov_b32 s50, 0x1ffffe0
	s_mov_b64 s[20:21], 0x18619180
	s_mov_b64 s[22:23], 0x1948180
	s_mov_b64 s[24:25], 0x1863a180
	s_mov_b64 s[26:27], 0x1969180
	s_mov_b64 s[30:31], 0x18619200
	s_mov_b64 s[34:35], 0x1948200
	s_mov_b64 s[36:37], 0x1863a200
	s_mov_b64 s[38:39], 0x1969200
	s_branch .LBB0_1010
.LBB0_1009:
	s_cmpk_lg_i32 s33, 0x100
	s_cbranch_scc1 .Lsk5_nox
	v_lshl_add_u32 v56, v25, 4, s45
	s_xor_b32 s56, s45, 0x10000
	v_lshl_add_u32 v57, v25, 4, s56
	s_barrier
	s_nop 7
	ds_write_b128 v56, v[2:5]
	ds_write_b128 v56, v[6:9] offset:4096
	ds_write_b128 v56, v[10:13] offset:8192
	ds_write_b128 v56, v[14:17] offset:12288
	s_waitcnt lgkmcnt(0)
	s_barrier
	ds_read_b128 v[58:61], v57
	ds_read_b128 v[62:65], v57 offset:4096
	ds_read_b128 v[66:69], v57 offset:8192
	ds_read_b128 v[70:73], v57 offset:12288
	s_waitcnt lgkmcnt(0)
	v_pk_add_f32 v[2:3], v[2:3], v[58:59]
	v_pk_add_f32 v[4:5], v[4:5], v[60:61]
	v_pk_add_f32 v[6:7], v[6:7], v[62:63]
	v_pk_add_f32 v[8:9], v[8:9], v[64:65]
	v_pk_add_f32 v[10:11], v[10:11], v[66:67]
	v_pk_add_f32 v[12:13], v[12:13], v[68:69]
	v_pk_add_f32 v[14:15], v[14:15], v[70:71]
	v_pk_add_f32 v[16:17], v[16:17], v[72:73]

; #define LAS __attribute__((address_space(3)))
; #define GLDS_STAGE(st, kt_) do { \
;         _Pragma("unroll") for (int i_ = 0; i_ < FI; ++i_) { \
;             glds16(ap + (size_t)(32 * i_) * lda + (kt_) * 64, l3a + (st) + tid * 16 + i_ * 4096); \
;             glds16(bp + (size_t)(32 * i_) * ldb + (kt_) * 64, l3a + (st) + OPB + tid * 16 + i_ * 4096); } } while (0)
; #define GLDS_STAGE(st, kt_) do { \
;         _Pragma("unroll") for (int i_ = 0; i_ < 4; ++i_) { \
;             glds16(ap + (size_t)(64 * i_) * lda + (kt_) * 64, l3a + (st) + tid * 16 + i_ * 8192); \
;             glds16(bp + (size_t)(64 * i_) * ldb + (kt_) * 64, l3a + (st) + 32768 + tid * 16 + i_ * 8192); } } while (0)
; template <int WT, class Epi>
; DEV void gemm_tile(const bf16_t* __restrict__ A, int lda, const bf16_t* __restrict__ Bt, int ldb, int K, unsigned char* lds, const Epi& epi) {
;     ...
;     const int lrow = tid >> 3, lcs = (tid & 7) ^ (lrow & 7);
;     const bf16_t* ap = A + (size_t)lrow * lda + lcs * 8;
;     const bf16_t* bp = Bt + (size_t)lrow * ldb + lcs * 8;
;     const unsigned l3a = (unsigned)(size_t)(LAS unsigned char*)lds;
;     const int nk = K >> 6;
;     ...
;     constexpr int NSTG = 65536 / STB;
; #pragma unroll
;     for (int s_ = 0; s_ < NSTG - 1; ++s_) if (s_ < nk) GLDS_STAGE(s_ * STB, s_);
;     const int aoff = (wr * WT + fr) * 128, boff = OPB + (wc * WT + fr) * 128, sw = fr & 7;
;     int cur = 0, nxt = (NSTG - 1) * STB;
;     for (int kt = 0; kt < nk; ++kt) {
;         if (NSTG == 4 && kt + 2 < nk) { if (FI == 2) asm volatile("s_waitcnt vmcnt(8)" ::: "memory"); else asm volatile("s_waitcnt vmcnt(0)" ::: "memory"); }
;         else asm volatile("s_waitcnt vmcnt(0)" ::: "memory");
;         __syncthreads();
;         if (kt + NSTG - 1 < nk) GLDS_STAGE(nxt, kt + NSTG - 1);
; #pragma unroll
;         for (int kh = 0; kh < 2; ++kh) {
;             bf16x8 af[FI], bfr[FI];
;             const int ch = ((kh * 4 + fq) ^ sw) << 4;
; #pragma unroll
;             for (int i = 0; i < FI; ++i) { af[i] = *(const bf16x8*)(lds + cur + aoff + i * 2048 + ch); bfr[i] = *(const bf16x8*)(lds + cur + boff + i * 2048 + ch); }
; #pragma unroll
;             for (int mi = 0; mi < FI; ++mi)
; #pragma unroll
;                 for (int ni = 0; ni < FI; ++ni) acc[mi][ni] = __builtin_amdgcn_mfma_f32_16x16x32_bf16(bfr[ni], af[mi], acc[mi][ni], 0, 0, 0);
.LBB0_1010:
	s_and_b32 s51, s6, 7
	s_ashr_i32 s53, s6, 3
	s_mul_i32 s6, s51, 0x21000
	v_mov_b32_e32 v25, v1
	s_add_i32 s52, s6, 0x1080000
	s_lshl_b32 s6, s52, 1
	v_ashrrev_i32_e32 v13, 3, v25
	v_xor_b32_e32 v8, v13, v25
	v_lshl_add_u64 v[2:3], v[174:175], 0, s[6:7]
	v_lshlrev_b32_e32 v8, 4, v8
	v_lshlrev_b32_e32 v27, 4, v25
	v_mad_i64_i32 v[4:5], s[40:41], s53, v24, v[170:171]
	v_mad_i64_i32 v[2:3], s[40:41], v13, s49, v[2:3]
	v_and_b32_e32 v18, 0x70, v8
	v_add_u32_e32 v18, s99, v18
	v_add_u32_e32 v28, 0x2000, v27
	v_add_u32_e32 v8, s45, v27
	v_lshl_add_u64 v[2:3], v[2:3], 0, v[18:19]
	v_mad_i64_i32 v[4:5], s[40:41], v13, s49, v[4:5]
	v_add_u32_e32 v9, s45, v28
	v_readfirstlane_b32 s6, v8
	s_mov_b32 s14, m0
	s_mov_b32 m0, s6
	s_nop 0
	global_load_lds_dwordx4 v[2:3], off
	s_mov_b32 m0, s14
	v_lshl_add_u64 v[4:5], v[4:5], 0, v[18:19]
	v_readfirstlane_b32 s14, v9
	s_mov_b32 s15, m0
	s_mov_b32 m0, s14
	s_nop 0
	global_load_lds_dwordx4 v[4:5], off
	s_mov_b32 m0, s15
	v_lshl_add_u64 v[8:9], v[2:3], 0, s[8:9]
	s_addk_i32 s6, 0x1000
	s_mov_b32 s15, m0
	s_mov_b32 m0, s6
	s_nop 0
	global_load_lds_dwordx4 v[8:9], off
	s_mov_b32 m0, s15
	v_lshl_add_u64 v[8:9], v[4:5], 0, s[8:9]
	s_add_i32 s6, s14, 0x1000
	s_mov_b32 s14, m0
	s_mov_b32 m0, s6
	s_nop 0
	global_load_lds_dwordx4 v[8:9], off
	s_mov_b32 m0, s14
	v_add_u32_e32 v14, s47, v27
	v_lshl_add_u64 v[8:9], v[2:3], 0, s[10:11]
	v_add_u32_e32 v15, s47, v28
	v_readfirstlane_b32 s6, v14
	s_mov_b32 s14, m0
	s_mov_b32 m0, s6
	s_nop 0
	global_load_lds_dwordx4 v[8:9], off
	s_mov_b32 m0, s14
	v_lshl_add_u64 v[10:11], v[4:5], 0, s[10:11]
	v_readfirstlane_b32 s14, v15
	s_mov_b32 s15, m0
	s_mov_b32 m0, s14
	s_nop 0
	global_load_lds_dwordx4 v[10:11], off
	s_mov_b32 m0, s15
	v_lshl_add_u64 v[8:9], v[2:3], 0, s[12:13]
	s_addk_i32 s6, 0x1000
	s_mov_b32 s15, m0
	s_mov_b32 m0, s6
	s_nop 0
	global_load_lds_dwordx4 v[8:9], off
	s_mov_b32 m0, s15
	v_lshl_add_u64 v[8:9], v[4:5], 0, s[12:13]
	s_add_i32 s6, s14, 0x1000
	s_mov_b32 s14, m0
	s_mov_b32 m0, s6
	s_nop 0
	global_load_lds_dwordx4 v[8:9], off
	s_mov_b32 m0, s14
	v_add_u32_e32 v14, s48, v27
	v_lshl_add_u64 v[8:9], v[2:3], 0, s[16:17]
	v_add_u32_e32 v15, s48, v28
	v_readfirstlane_b32 s6, v14
	s_mov_b32 s14, m0
	s_mov_b32 m0, s6
	s_nop 0
	global_load_lds_dwordx4 v[8:9], off
	s_mov_b32 m0, s14
	v_lshl_add_u64 v[10:11], v[4:5], 0, s[16:17]
	v_readfirstlane_b32 s14, v15
	s_mov_b32 s15, m0
	s_mov_b32 m0, s14
	s_nop 0
	global_load_lds_dwordx4 v[10:11], off
	s_mov_b32 m0, s15
	v_lshl_add_u64 v[2:3], v[2:3], 0, s[18:19]
	s_addk_i32 s6, 0x1000
	s_mov_b32 s15, m0
	s_mov_b32 m0, s6
	s_nop 0
	global_load_lds_dwordx4 v[2:3], off
	s_mov_b32 m0, s15
	v_lshl_add_u64 v[2:3], v[4:5], 0, s[18:19]
	v_and_b32_e32 v12, 15, v25
	s_add_i32 s6, s14, 0x1000
	s_mov_b32 s14, m0
	s_mov_b32 m0, s6
	s_nop 0
	global_load_lds_dwordx4 v[2:3], off
	s_mov_b32 m0, s14
	v_lshrrev_b32_e32 v2, 2, v25
	v_and_or_b32 v2, v2, s50, v12
	v_lshlrev_b32_e32 v31, 7, v2
	v_lshrrev_b32_e32 v2, 1, v25
	v_and_b32_e32 v32, 32, v2
	v_lshrrev_b32_e32 v26, 4, v25
	v_or_b32_e32 v2, v32, v12
	v_and_b32_e32 v29, 7, v25
	v_bfe_u32 v30, v25, 4, 2
	v_lshlrev_b32_e32 v33, 7, v2
	v_bitop3_b32 v2, v26, v29, 3 bitop3:0x6c
	v_lshlrev_b32_e32 v34, 4, v2
	v_bitop3_b32 v2, v30, v29, 4 bitop3:0x36
	v_mad_i64_i32 v[6:7], s[40:41], v13, s49, 0
	v_lshlrev_b32_e32 v35, 4, v2
	v_bitop3_b32 v2, v13, 7, v25 bitop3:0x48
	v_lshlrev_b32_e32 v18, 4, v2
	v_add_u32_e32 v18, s99, v18
	v_mad_i64_i32 v[2:3], s[40:41], s53, v24, v[6:7]
	v_lshl_add_u64 v[20:21], v[158:159], 0, v[2:3]
	v_mad_u64_u32 v[2:3], s[40:41], s51, v24, v[6:7]
	v_lshl_add_u64 v[22:23], v[158:159], 0, v[2:3]
	s_mov_b32 s55, 0xc000
	s_mov_b32 s6, 0
	s_mov_b32 s54, 0
	v_mov_b32_e32 v6, v19
	v_mov_b32_e32 v7, v19
	v_mov_b32_e32 v8, v19
	v_mov_b32_e32 v9, v19
	v_mov_b32_e32 v2, v19
	v_mov_b32_e32 v3, v19
	v_mov_b32_e32 v4, v19
	v_mov_b32_e32 v5, v19
	v_mov_b32_e32 v10, v19
	v_mov_b32_e32 v11, v19
	v_mov_b32_e32 v12, v19
	v_mov_b32_e32 v13, v19
	v_mov_b32_e32 v14, v19
	v_mov_b32_e32 v15, v19
	v_mov_b32_e32 v16, v19
	v_mov_b32_e32 v17, v19
	s_branch .LBB0_1012
.LBB0_1011:
	s_addk_i32 s6, 0x4000
	s_cmp_lg_u32 s6, 0x10000
	s_cselect_b32 s55, s6, 0
	s_add_i32 s6, s45, s55
	v_add_u32_e32 v52, s6, v33
	v_add_u32_e32 v40, v52, v34
	ds_read_b128 v[36:39], v40 offset:8192
	v_add_u32_e32 v53, s6, v31
	v_add_u32_e32 v48, v53, v34
	ds_read_b128 v[40:43], v40 offset:10240
	ds_read_b128 v[44:47], v48
	ds_read_b128 v[48:51], v48 offset:2048
	s_waitcnt lgkmcnt(1)
	v_mfma_f32_16x16x32_bf16 v[6:9], v[40:43], v[44:47], v[6:9]
	s_add_i32 s6, s55, 0x4000
	s_cmp_lg_u32 s6, 0x10000
	s_cselect_b32 s6, s6, 0
	v_mfma_f32_16x16x32_bf16 v[2:5], v[36:39], v[44:47], v[2:5]
	s_add_i32 s54, s40, 1
	v_lshl_add_u64 v[20:21], v[20:21], 0, s[16:17]
	s_cmp_lg_u32 s54, s96
	s_waitcnt lgkmcnt(0)
	v_mfma_f32_16x16x32_bf16 v[36:39], v[36:39], v[48:51], v[10:13]
	v_lshl_add_u64 v[22:23], v[22:23], 0, s[16:17]
	s_nop 1
	v_add_u32_e32 v10, v52, v35
	ds_read_b128 v[44:47], v10 offset:8192
	v_mfma_f32_16x16x32_bf16 v[40:43], v[40:43], v[48:51], v[14:17]
	s_nop 2
	v_add_u32_e32 v14, v53, v35
	ds_read_b128 v[48:51], v10 offset:10240
	ds_read_b128 v[10:13], v14
	ds_read_b128 v[52:55], v14 offset:2048
	s_waitcnt lgkmcnt(1)
	v_mfma_f32_16x16x32_bf16 v[14:17], v[44:47], v[10:13], v[2:5]
	v_mfma_f32_16x16x32_bf16 v[10:13], v[48:51], v[10:13], v[6:9]
	s_waitcnt lgkmcnt(0)
	v_mfma_f32_16x16x32_bf16 v[2:5], v[44:47], v[52:55], v[36:39]
	v_mfma_f32_16x16x32_bf16 v[6:9], v[48:51], v[52:55], v[40:43]
	s_cbranch_scc0 .LBB0_1009
.LBB0_1012:
	s_cmp_gt_u32 s54, s97
	s_cselect_b64 s[40:41], -1, 0
	s_mov_b64 s[42:43], -1
	s_and_b64 vcc, exec, s[40:41]
	s_cbranch_vccz .LBB0_1014
	s_waitcnt vmcnt(0)
	s_mov_b64 s[42:43], 0

; #define GLDS_STAGE(st, kt_) do { \
;         _Pragma("unroll") for (int i_ = 0; i_ < FI; ++i_) { \
;             glds16(ap + (size_t)(32 * i_) * lda + (kt_) * 64, l3a + (st) + tid * 16 + i_ * 4096); \
;             glds16(bp + (size_t)(32 * i_) * ldb + (kt_) * 64, l3a + (st) + OPB + tid * 16 + i_ * 4096); } } while (0)
; #define GLDS_STAGE(st, kt_) do { \
;         _Pragma("unroll") for (int i_ = 0; i_ < 4; ++i_) { \
;             glds16(ap + (size_t)(64 * i_) * lda + (kt_) * 64, l3a + (st) + tid * 16 + i_ * 8192); \
;             glds16(bp + (size_t)(64 * i_) * ldb + (kt_) * 64, l3a + (st) + 32768 + tid * 16 + i_ * 8192); } } while (0)
; template <int WT, class Epi>
; DEV void gemm_tile(const bf16_t* __restrict__ A, int lda, const bf16_t* __restrict__ Bt, int ldb, int K, unsigned char* lds, const Epi& epi) {
;     ...
;         if (NSTG == 4 && kt + 2 < nk) { if (FI == 2) asm volatile("s_waitcnt vmcnt(8)" ::: "memory"); else asm volatile("s_waitcnt vmcnt(0)" ::: "memory"); }
;         else asm volatile("s_waitcnt vmcnt(0)" ::: "memory");
;         __syncthreads();
;         if (kt + NSTG - 1 < nk) GLDS_STAGE(nxt, kt + NSTG - 1);
.LBB0_1016:
	s_cmp_gt_u32 s54, s98
	s_waitcnt lgkmcnt(0)
	s_barrier
	s_cbranch_scc1 .LBB0_1018
	s_add_i32 s14, s55, s45
	v_lshl_add_u64 v[36:37], v[22:23], 0, v[18:19]
	v_add_u32_e32 v44, s14, v27
	v_lshl_add_u64 v[38:39], v[36:37], 0, s[20:21]
	v_lshl_add_u64 v[40:41], v[20:21], 0, v[18:19]
	v_add_u32_e32 v45, s14, v28
	v_readfirstlane_b32 s14, v44
	s_mov_b32 s15, m0
	s_mov_b32 m0, s14
	s_nop 0
	global_load_lds_dwordx4 v[38:39], off
	s_mov_b32 m0, s15
	v_lshl_add_u64 v[42:43], v[40:41], 0, s[22:23]
	v_readfirstlane_b32 s15, v45
	s_mov_b32 s42, m0
	s_mov_b32 m0, s15
	s_nop 0
	global_load_lds_dwordx4 v[42:43], off
	s_mov_b32 m0, s42
	v_lshl_add_u64 v[36:37], v[36:37], 0, s[24:25]
	s_addk_i32 s14, 0x1000
	s_mov_b32 s42, m0
	s_mov_b32 m0, s14
	s_nop 0
	global_load_lds_dwordx4 v[36:37], off
	s_mov_b32 m0, s42
	v_lshl_add_u64 v[36:37], v[40:41], 0, s[26:27]
	s_add_i32 s14, s15, 0x1000
	s_mov_b32 s15, m0
	s_mov_b32 m0, s14
	s_nop 0
	global_load_lds_dwordx4 v[36:37], off
	s_mov_b32 m0, s15

; #define GLDS_STAGE(st, kt_) do { \
;         _Pragma("unroll") for (int i_ = 0; i_ < FI; ++i_) { \
;             glds16(ap + (size_t)(32 * i_) * lda + (kt_) * 64, l3a + (st) + tid * 16 + i_ * 4096); \
;             glds16(bp + (size_t)(32 * i_) * ldb + (kt_) * 64, l3a + (st) + OPB + tid * 16 + i_ * 4096); } } while (0)
; #define GLDS_STAGE(st, kt_) do { \
;         _Pragma("unroll") for (int i_ = 0; i_ < 4; ++i_) { \
;             glds16(ap + (size_t)(64 * i_) * lda + (kt_) * 64, l3a + (st) + tid * 16 + i_ * 8192); \
;             glds16(bp + (size_t)(64 * i_) * ldb + (kt_) * 64, l3a + (st) + 32768 + tid * 16 + i_ * 8192); } } while (0)
; template <int WT, class Epi>
; DEV void gemm_tile(const bf16_t* __restrict__ A, int lda, const bf16_t* __restrict__ Bt, int ldb, int K, unsigned char* lds, const Epi& epi) {
;     ...
;     for (int kt = 0; kt < nk; ++kt) {
;         if (NSTG == 4 && kt + 2 < nk) { if (FI == 2) asm volatile("s_waitcnt vmcnt(8)" ::: "memory"); else asm volatile("s_waitcnt vmcnt(0)" ::: "memory"); }
;         else asm volatile("s_waitcnt vmcnt(0)" ::: "memory");
;         __syncthreads();
;         if (kt + NSTG - 1 < nk) GLDS_STAGE(nxt, kt + NSTG - 1);
.LBB0_1022:
	s_add_i32 s40, s54, 1
	s_cmp_gt_u32 s40, s98
	s_barrier
	s_cbranch_scc1 .LBB0_1011
	v_lshl_add_u64 v[36:37], v[22:23], 0, v[18:19]
	v_add_u32_e32 v44, s55, v27
	v_lshl_add_u64 v[38:39], v[36:37], 0, s[30:31]
	v_lshl_add_u64 v[40:41], v[20:21], 0, v[18:19]
	v_add_u32_e32 v45, s55, v28
	v_readfirstlane_b32 s14, v44
	s_mov_b32 s15, m0
	s_mov_b32 m0, s14
	s_nop 0
	global_load_lds_dwordx4 v[38:39], off
	s_mov_b32 m0, s15
	v_lshl_add_u64 v[42:43], v[40:41], 0, s[34:35]
	v_readfirstlane_b32 s15, v45
	s_mov_b32 s41, m0
	s_mov_b32 m0, s15
	s_nop 0
	global_load_lds_dwordx4 v[42:43], off
	s_mov_b32 m0, s41
	v_lshl_add_u64 v[36:37], v[36:37], 0, s[36:37]
	s_addk_i32 s14, 0x1000
	s_mov_b32 s41, m0
	s_mov_b32 m0, s14
	s_nop 0
	global_load_lds_dwordx4 v[36:37], off
	s_mov_b32 m0, s41
	v_lshl_add_u64 v[36:37], v[40:41], 0, s[38:39]
	s_add_i32 s14, s15, 0x1000
	s_mov_b32 s15, m0
	s_mov_b32 m0, s14
	s_nop 0
	global_load_lds_dwordx4 v[36:37], off
	s_mov_b32 m0, s15
	s_branch .LBB0_1011

; #define VLOOP(t, N) for (int t##0_ = 2 * bid, t = min(t##0_ + vb, (N) - 1); t##0_ < (N); t##0_ += VG, t = min(t##0_ + vb, (N) - 1))
; template <int WT, class Epi>
; DEV void gemm_tile(const bf16_t* __restrict__ A, int lda, const bf16_t* __restrict__ Bt, int ldb, int K, unsigned char* lds, const Epi& epi) {
;     ...
;         nxt = cur; cur += STB; if (cur == NSTG * STB) cur = 0;
;     }
;     ...
;     __syncthreads();
; __global__ void __launch_bounds__(512) hymba_fwd(Params p) {
;     ...
;     if (IN_PH(7)) { PH_LOCALS
;         VLOOP(t, 8 * 32) { const int mt = t & 7, nt = t >> 3;
;             EpiBfS e{qx + (size_t)(TP + mt * 64) * LDB + nt * 64, LDB};
;             gemm_tile<32>(hbuf + (size_t)(TP + mt * 64) * LDB, LDB, Wt_cq + (size_t)nt * 64 * LDB, LDB, D, vlds, e);
.LBB0_1133:
	s_or_b64 exec, exec, s[4:5]
	s_waitcnt lgkmcnt(0)
	s_barrier
	s_load_dwordx2 s[4:5], s[0:1], 0xd0
	s_mov_b64 s[6:7], 0x1cc29000
	v_lshl_add_u64 v[132:133], v[158:159], 0, s[6:7]
	s_waitcnt lgkmcnt(0)
	s_cmp_lt_i32 s4, 8
	s_cselect_b64 s[8:9], -1, 0
	s_cmp_gt_i32 s5, 7
	s_cselect_b64 s[4:5], -1, 0
	s_and_b64 s[4:5], s[8:9], s[4:5]
	s_andn2_b64 vcc, exec, s[4:5]
	s_cbranch_vccnz .LBB0_1151
	v_mov_b32_e32 v1, v0
	s_movk_i32 s96, 0x7f
	s_cmpk_eq_i32 s33, 0x100
	s_cselect_b32 s96, 0xff, s96
	s_cmp_gt_i32 s2, s96
	v_readfirstlane_b32 s4, v1
	s_cbranch_scc1 .LBB0_1151
	s_ashr_i32 s42, s4, 8
	s_lshl_b32 s44, s2, 1
	s_lshl_b32 s43, s42, 16
	s_add_i32 s4, s42, s44
	s_min_i32 s38, s4, 0xff
	s_mov_b32 s96, 32
	s_mov_b32 s97, 29
	s_mov_b32 s98, 28
	s_mov_b32 s99, 0
	s_cmpk_lg_i32 s33, 0x100
	s_cbranch_scc1 .Lsk7a_hdr
	s_mov_b32 s38, s2
	s_mov_b32 s96, 16
	s_mov_b32 s97, 13
	s_mov_b32 s98, 12
	s_lshl_b32 s99, s42, 11
.Lsk7a_hdr:
	v_and_b32_e32 v1, 0xff, v0
	s_or_b32 s45, s43, 0x4000
	s_or_b32 s46, s43, 0x8000
	s_mov_b32 s5, 0
	v_mov_b32_e32 v24, 0x42000
	s_movk_i32 s47, 0x1080
	v_mov_b32_e32 v19, 0
	s_mov_b64 s[6:7], 0x21000
	s_mov_b64 s[8:9], 0x80
	s_mov_b64 s[10:11], 0x21080
	s_mov_b64 s[12:13], 0x100
	s_mov_b64 s[16:17], 0x21100
	s_mov_b32 s48, 0x1ffffe0
	s_mov_b64 s[18:19], 0x6418180
	s_mov_b64 s[20:21], 0x2188180
	s_mov_b64 s[22:23], 0x6439180
	s_mov_b64 s[24:25], 0x21a9180
	s_mov_b64 s[26:27], 0x6418200
	s_mov_b64 s[30:31], 0x2188200
	s_mov_b64 s[34:35], 0x6439200
	s_mov_b64 s[36:37], 0x21a9200
	s_branch .LBB0_1137
.LBB0_1136:
	s_cmpk_lg_i32 s33, 0x100
	s_cbranch_scc1 .Lsk7a_nox
	v_lshl_add_u32 v56, v25, 4, s43
	s_xor_b32 s53, s43, 0x10000
	v_lshl_add_u32 v57, v25, 4, s53
	s_barrier
	s_nop 7
	ds_write_b128 v56, v[2:5]
	ds_write_b128 v56, v[6:9] offset:4096
	ds_write_b128 v56, v[10:13] offset:8192
	ds_write_b128 v56, v[14:17] offset:12288
	s_waitcnt lgkmcnt(0)
	s_barrier
	ds_read_b128 v[58:61], v57
	ds_read_b128 v[62:65], v57 offset:4096
	ds_read_b128 v[66:69], v57 offset:8192
	ds_read_b128 v[70:73], v57 offset:12288
	s_waitcnt lgkmcnt(0)
	v_pk_add_f32 v[2:3], v[2:3], v[58:59]
	v_pk_add_f32 v[4:5], v[4:5], v[60:61]
	v_pk_add_f32 v[6:7], v[6:7], v[62:63]
	v_pk_add_f32 v[8:9], v[8:9], v[64:65]
	v_pk_add_f32 v[10:11], v[10:11], v[66:67]
	v_pk_add_f32 v[12:13], v[12:13], v[68:69]
	v_pk_add_f32 v[14:15], v[14:15], v[70:71]
	v_pk_add_f32 v[16:17], v[16:17], v[72:73]

; #define LAS __attribute__((address_space(3)))
; #define GLDS_STAGE(st, kt_) do { \
;         _Pragma("unroll") for (int i_ = 0; i_ < FI; ++i_) { \
;             glds16(ap + (size_t)(32 * i_) * lda + (kt_) * 64, l3a + (st) + tid * 16 + i_ * 4096); \
;             glds16(bp + (size_t)(32 * i_) * ldb + (kt_) * 64, l3a + (st) + OPB + tid * 16 + i_ * 4096); } } while (0)
; #define GLDS_STAGE(st, kt_) do { \
;         _Pragma("unroll") for (int i_ = 0; i_ < 4; ++i_) { \
;             glds16(ap + (size_t)(64 * i_) * lda + (kt_) * 64, l3a + (st) + tid * 16 + i_ * 8192); \
;             glds16(bp + (size_t)(64 * i_) * ldb + (kt_) * 64, l3a + (st) + 32768 + tid * 16 + i_ * 8192); } } while (0)
; template <int WT, class Epi>
; DEV void gemm_tile(const bf16_t* __restrict__ A, int lda, const bf16_t* __restrict__ Bt, int ldb, int K, unsigned char* lds, const Epi& epi) {
;     ...
;     const int lrow = tid >> 3, lcs = (tid & 7) ^ (lrow & 7);
;     const bf16_t* ap = A + (size_t)lrow * lda + lcs * 8;
;     const bf16_t* bp = Bt + (size_t)lrow * ldb + lcs * 8;
;     const unsigned l3a = (unsigned)(size_t)(LAS unsigned char*)lds;
;     const int nk = K >> 6;
;     ...
;     constexpr int NSTG = 65536 / STB;
; #pragma unroll
;     for (int s_ = 0; s_ < NSTG - 1; ++s_) if (s_ < nk) GLDS_STAGE(s_ * STB, s_);
;     const int aoff = (wr * WT + fr) * 128, boff = OPB + (wc * WT + fr) * 128, sw = fr & 7;
;     int cur = 0, nxt = (NSTG - 1) * STB;
;     for (int kt = 0; kt < nk; ++kt) {
;         if (NSTG == 4 && kt + 2 < nk) { if (FI == 2) asm volatile("s_waitcnt vmcnt(8)" ::: "memory"); else asm volatile("s_waitcnt vmcnt(0)" ::: "memory"); }
;         else asm volatile("s_waitcnt vmcnt(0)" ::: "memory");
;         __syncthreads();
;         if (kt + NSTG - 1 < nk) GLDS_STAGE(nxt, kt + NSTG - 1);
; #pragma unroll
;         for (int kh = 0; kh < 2; ++kh) {
;             bf16x8 af[FI], bfr[FI];
;             const int ch = ((kh * 4 + fq) ^ sw) << 4;
; #pragma unroll
;             for (int i = 0; i < FI; ++i) { af[i] = *(const bf16x8*)(lds + cur + aoff + i * 2048 + ch); bfr[i] = *(const bf16x8*)(lds + cur + boff + i * 2048 + ch); }
; #pragma unroll
;             for (int mi = 0; mi < FI; ++mi)
; #pragma unroll
;                 for (int ni = 0; ni < FI; ++ni) acc[mi][ni] = __builtin_amdgcn_mfma_f32_16x16x32_bf16(bfr[ni], af[mi], acc[mi][ni], 0, 0, 0);
.LBB0_1137:
	s_lshl_b32 s4, s38, 6
	s_and_b32 s4, s4, 0x1c0
	s_mulk_i32 s4, 0x840
	v_mov_b32_e32 v25, v1
	s_add_i32 s50, s4, 0x1080000
	s_lshl_b32 s4, s50, 1
	v_ashrrev_i32_e32 v13, 3, v25
	v_xor_b32_e32 v8, v13, v25
	s_ashr_i32 s49, s38, 3
	v_lshl_add_u64 v[2:3], v[166:167], 0, s[4:5]
	v_lshlrev_b32_e32 v8, 4, v8
	v_lshlrev_b32_e32 v27, 4, v25
	v_mad_i64_i32 v[4:5], s[40:41], s49, v24, v[164:165]
	v_mad_i64_i32 v[2:3], s[40:41], v13, s47, v[2:3]
	v_and_b32_e32 v18, 0x70, v8
	v_add_u32_e32 v18, s99, v18
	v_add_u32_e32 v28, 0x2000, v27
	v_add_u32_e32 v8, s43, v27
	v_lshl_add_u64 v[2:3], v[2:3], 0, v[18:19]
	v_mad_i64_i32 v[4:5], s[40:41], v13, s47, v[4:5]
	v_add_u32_e32 v9, s43, v28
	v_readfirstlane_b32 s4, v8
	s_mov_b32 s14, m0
	s_mov_b32 m0, s4
	s_nop 0
	global_load_lds_dwordx4 v[2:3], off
	s_mov_b32 m0, s14
	v_lshl_add_u64 v[4:5], v[4:5], 0, v[18:19]
	v_readfirstlane_b32 s14, v9
	s_mov_b32 s15, m0
	s_mov_b32 m0, s14
	s_nop 0
	global_load_lds_dwordx4 v[4:5], off
	s_mov_b32 m0, s15
	v_lshl_add_u64 v[8:9], v[2:3], 0, s[6:7]
	s_addk_i32 s4, 0x1000
	s_mov_b32 s15, m0
	s_mov_b32 m0, s4
	s_nop 0
	global_load_lds_dwordx4 v[8:9], off
	s_mov_b32 m0, s15
	v_lshl_add_u64 v[8:9], v[4:5], 0, s[6:7]
	s_add_i32 s4, s14, 0x1000
	s_mov_b32 s14, m0
	s_mov_b32 m0, s4
	s_nop 0
	global_load_lds_dwordx4 v[8:9], off
	s_mov_b32 m0, s14
	v_add_u32_e32 v14, s45, v27
	v_lshl_add_u64 v[8:9], v[2:3], 0, s[8:9]
	v_add_u32_e32 v15, s45, v28
	v_readfirstlane_b32 s4, v14
	s_mov_b32 s14, m0
	s_mov_b32 m0, s4
	s_nop 0
	global_load_lds_dwordx4 v[8:9], off
	s_mov_b32 m0, s14
	v_lshl_add_u64 v[10:11], v[4:5], 0, s[8:9]
	v_readfirstlane_b32 s14, v15
	s_mov_b32 s15, m0
	s_mov_b32 m0, s14
	s_nop 0
	global_load_lds_dwordx4 v[10:11], off
	s_mov_b32 m0, s15
	v_lshl_add_u64 v[8:9], v[2:3], 0, s[10:11]
	s_addk_i32 s4, 0x1000
	s_mov_b32 s15, m0
	s_mov_b32 m0, s4
	s_nop 0
	global_load_lds_dwordx4 v[8:9], off
	s_mov_b32 m0, s15
	v_lshl_add_u64 v[8:9], v[4:5], 0, s[10:11]
	s_add_i32 s4, s14, 0x1000
	s_mov_b32 s14, m0
	s_mov_b32 m0, s4
	s_nop 0
	global_load_lds_dwordx4 v[8:9], off
	s_mov_b32 m0, s14
	v_add_u32_e32 v14, s46, v27
	v_lshl_add_u64 v[8:9], v[2:3], 0, s[12:13]
	v_add_u32_e32 v15, s46, v28
	v_readfirstlane_b32 s4, v14
	s_mov_b32 s14, m0
	s_mov_b32 m0, s4
	s_nop 0
	global_load_lds_dwordx4 v[8:9], off
	s_mov_b32 m0, s14
	v_lshl_add_u64 v[10:11], v[4:5], 0, s[12:13]
	v_readfirstlane_b32 s14, v15
	s_mov_b32 s15, m0
	s_mov_b32 m0, s14
	s_nop 0
	global_load_lds_dwordx4 v[10:11], off
	s_mov_b32 m0, s15
	v_lshl_add_u64 v[2:3], v[2:3], 0, s[16:17]
	s_addk_i32 s4, 0x1000
	s_mov_b32 s15, m0
	s_mov_b32 m0, s4
	s_nop 0
	global_load_lds_dwordx4 v[2:3], off
	s_mov_b32 m0, s15
	v_lshl_add_u64 v[2:3], v[4:5], 0, s[16:17]
	v_and_b32_e32 v12, 15, v25
	s_add_i32 s4, s14, 0x1000
	s_mov_b32 s14, m0
	s_mov_b32 m0, s4
	s_nop 0
	global_load_lds_dwordx4 v[2:3], off
	s_mov_b32 m0, s14
	v_lshrrev_b32_e32 v2, 2, v25
	v_and_or_b32 v2, v2, s48, v12
	v_lshlrev_b32_e32 v31, 7, v2
	v_lshrrev_b32_e32 v2, 1, v25
	v_and_b32_e32 v32, 32, v2
	v_lshrrev_b32_e32 v26, 4, v25
	v_or_b32_e32 v2, v32, v12
	v_and_b32_e32 v29, 7, v25
	v_bfe_u32 v30, v25, 4, 2
	v_lshlrev_b32_e32 v33, 7, v2
	v_bitop3_b32 v2, v26, v29, 3 bitop3:0x6c
	v_lshlrev_b32_e32 v34, 4, v2
	v_bitop3_b32 v2, v30, v29, 4 bitop3:0x36
	v_mad_i64_i32 v[6:7], s[40:41], v13, s47, 0
	v_lshlrev_b32_e32 v35, 4, v2
	v_bitop3_b32 v2, v13, 7, v25 bitop3:0x48
	v_lshlrev_b32_e32 v18, 4, v2
	v_add_u32_e32 v18, s99, v18
	v_mad_i64_i32 v[2:3], s[40:41], s49, v24, v[6:7]
	s_and_b32 s4, s38, 7
	v_lshl_add_u64 v[20:21], v[158:159], 0, v[2:3]
	v_mad_u64_u32 v[2:3], s[38:39], s4, v24, v[6:7]
	v_lshl_add_u64 v[22:23], v[158:159], 0, v[2:3]
	s_mov_b32 s52, 0xc000
	s_mov_b32 s4, 0
	s_mov_b32 s51, 0
	v_mov_b32_e32 v6, v19
	v_mov_b32_e32 v7, v19
	v_mov_b32_e32 v8, v19
	v_mov_b32_e32 v9, v19
	v_mov_b32_e32 v2, v19
	v_mov_b32_e32 v3, v19
	v_mov_b32_e32 v4, v19
	v_mov_b32_e32 v5, v19
	v_mov_b32_e32 v10, v19
	v_mov_b32_e32 v11, v19
	v_mov_b32_e32 v12, v19
	v_mov_b32_e32 v13, v19
	v_mov_b32_e32 v14, v19
	v_mov_b32_e32 v15, v19
	v_mov_b32_e32 v16, v19
	v_mov_b32_e32 v17, v19
	s_branch .LBB0_1139
.LBB0_1138:
	s_addk_i32 s4, 0x4000
	s_cmp_lg_u32 s4, 0x10000
	s_cselect_b32 s52, s4, 0
	s_add_i32 s4, s43, s52
	v_add_u32_e32 v52, s4, v33
	v_add_u32_e32 v40, v52, v34
	ds_read_b128 v[36:39], v40 offset:8192
	v_add_u32_e32 v53, s4, v31
	v_add_u32_e32 v48, v53, v34
	ds_read_b128 v[40:43], v40 offset:10240
	ds_read_b128 v[44:47], v48
	ds_read_b128 v[48:51], v48 offset:2048
	s_waitcnt lgkmcnt(1)
	v_mfma_f32_16x16x32_bf16 v[6:9], v[40:43], v[44:47], v[6:9]
	s_add_i32 s4, s52, 0x4000
	s_cmp_lg_u32 s4, 0x10000
	s_cselect_b32 s4, s4, 0
	v_mfma_f32_16x16x32_bf16 v[2:5], v[36:39], v[44:47], v[2:5]
	s_add_i32 s51, s38, 1
	v_lshl_add_u64 v[20:21], v[20:21], 0, s[12:13]
	s_cmp_lg_u32 s51, s96
	s_waitcnt lgkmcnt(0)
	v_mfma_f32_16x16x32_bf16 v[36:39], v[36:39], v[48:51], v[10:13]
	v_lshl_add_u64 v[22:23], v[22:23], 0, s[12:13]
	s_nop 1
	v_add_u32_e32 v10, v52, v35
	ds_read_b128 v[44:47], v10 offset:8192
	v_mfma_f32_16x16x32_bf16 v[40:43], v[40:43], v[48:51], v[14:17]
	s_nop 2
	v_add_u32_e32 v14, v53, v35
	ds_read_b128 v[48:51], v10 offset:10240
	ds_read_b128 v[10:13], v14
	ds_read_b128 v[52:55], v14 offset:2048
	s_waitcnt lgkmcnt(1)
	v_mfma_f32_16x16x32_bf16 v[14:17], v[44:47], v[10:13], v[2:5]
	v_mfma_f32_16x16x32_bf16 v[10:13], v[48:51], v[10:13], v[6:9]
	s_waitcnt lgkmcnt(0)
	v_mfma_f32_16x16x32_bf16 v[2:5], v[44:47], v[52:55], v[36:39]
	v_mfma_f32_16x16x32_bf16 v[6:9], v[48:51], v[52:55], v[40:43]
	s_cbranch_scc0 .LBB0_1136
.LBB0_1139:
	s_cmp_gt_u32 s51, s97
	s_cselect_b64 s[38:39], -1, 0
	s_mov_b64 s[40:41], -1
	s_and_b64 vcc, exec, s[38:39]
	s_cbranch_vccz .LBB0_1141
	s_waitcnt vmcnt(0)
	s_mov_b64 s[40:41], 0

; #define GLDS_STAGE(st, kt_) do { \
;         _Pragma("unroll") for (int i_ = 0; i_ < FI; ++i_) { \
;             glds16(ap + (size_t)(32 * i_) * lda + (kt_) * 64, l3a + (st) + tid * 16 + i_ * 4096); \
;             glds16(bp + (size_t)(32 * i_) * ldb + (kt_) * 64, l3a + (st) + OPB + tid * 16 + i_ * 4096); } } while (0)
; #define GLDS_STAGE(st, kt_) do { \
;         _Pragma("unroll") for (int i_ = 0; i_ < 4; ++i_) { \
;             glds16(ap + (size_t)(64 * i_) * lda + (kt_) * 64, l3a + (st) + tid * 16 + i_ * 8192); \
;             glds16(bp + (size_t)(64 * i_) * ldb + (kt_) * 64, l3a + (st) + 32768 + tid * 16 + i_ * 8192); } } while (0)
; template <int WT, class Epi>
; DEV void gemm_tile(const bf16_t* __restrict__ A, int lda, const bf16_t* __restrict__ Bt, int ldb, int K, unsigned char* lds, const Epi& epi) {
;     ...
;         if (NSTG == 4 && kt + 2 < nk) { if (FI == 2) asm volatile("s_waitcnt vmcnt(8)" ::: "memory"); else asm volatile("s_waitcnt vmcnt(0)" ::: "memory"); }
;         else asm volatile("s_waitcnt vmcnt(0)" ::: "memory");
;         __syncthreads();
;         if (kt + NSTG - 1 < nk) GLDS_STAGE(nxt, kt + NSTG - 1);
.LBB0_1143:
	s_cmp_gt_u32 s51, s98
	s_barrier
	s_cbranch_scc1 .LBB0_1145
	s_add_i32 s14, s52, s43
	v_lshl_add_u64 v[36:37], v[22:23], 0, v[18:19]
	v_add_u32_e32 v44, s14, v27
	v_lshl_add_u64 v[38:39], v[36:37], 0, s[18:19]
	v_lshl_add_u64 v[40:41], v[20:21], 0, v[18:19]
	v_add_u32_e32 v45, s14, v28
	v_readfirstlane_b32 s14, v44
	s_mov_b32 s15, m0
	s_mov_b32 m0, s14
	s_nop 0
	global_load_lds_dwordx4 v[38:39], off
	s_mov_b32 m0, s15
	v_lshl_add_u64 v[42:43], v[40:41], 0, s[20:21]
	v_readfirstlane_b32 s15, v45
	s_mov_b32 s40, m0
	s_mov_b32 m0, s15
	s_nop 0
	global_load_lds_dwordx4 v[42:43], off
	s_mov_b32 m0, s40
	v_lshl_add_u64 v[36:37], v[36:37], 0, s[22:23]
	s_addk_i32 s14, 0x1000
	s_mov_b32 s40, m0
	s_mov_b32 m0, s14
	s_nop 0
	global_load_lds_dwordx4 v[36:37], off
	s_mov_b32 m0, s40
	v_lshl_add_u64 v[36:37], v[40:41], 0, s[24:25]
	s_add_i32 s14, s15, 0x1000
	s_mov_b32 s15, m0
	s_mov_b32 m0, s14
	s_nop 0
	global_load_lds_dwordx4 v[36:37], off
	s_mov_b32 m0, s15

; #define GLDS_STAGE(st, kt_) do { \
;         _Pragma("unroll") for (int i_ = 0; i_ < FI; ++i_) { \
;             glds16(ap + (size_t)(32 * i_) * lda + (kt_) * 64, l3a + (st) + tid * 16 + i_ * 4096); \
;             glds16(bp + (size_t)(32 * i_) * ldb + (kt_) * 64, l3a + (st) + OPB + tid * 16 + i_ * 4096); } } while (0)
; #define GLDS_STAGE(st, kt_) do { \
;         _Pragma("unroll") for (int i_ = 0; i_ < 4; ++i_) { \
;             glds16(ap + (size_t)(64 * i_) * lda + (kt_) * 64, l3a + (st) + tid * 16 + i_ * 8192); \
;             glds16(bp + (size_t)(64 * i_) * ldb + (kt_) * 64, l3a + (st) + 32768 + tid * 16 + i_ * 8192); } } while (0)
; template <int WT, class Epi>
; DEV void gemm_tile(const bf16_t* __restrict__ A, int lda, const bf16_t* __restrict__ Bt, int ldb, int K, unsigned char* lds, const Epi& epi) {
;     ...
;     for (int kt = 0; kt < nk; ++kt) {
;         if (NSTG == 4 && kt + 2 < nk) { if (FI == 2) asm volatile("s_waitcnt vmcnt(8)" ::: "memory"); else asm volatile("s_waitcnt vmcnt(0)" ::: "memory"); }
;         else asm volatile("s_waitcnt vmcnt(0)" ::: "memory");
;         __syncthreads();
;         if (kt + NSTG - 1 < nk) GLDS_STAGE(nxt, kt + NSTG - 1);
.LBB0_1149:
	s_add_i32 s38, s51, 1
	s_cmp_gt_u32 s38, s98
	s_barrier
	s_cbranch_scc1 .LBB0_1138
	v_lshl_add_u64 v[36:37], v[22:23], 0, v[18:19]
	v_add_u32_e32 v44, s52, v27
	v_lshl_add_u64 v[38:39], v[36:37], 0, s[26:27]
	v_lshl_add_u64 v[40:41], v[20:21], 0, v[18:19]
	v_add_u32_e32 v45, s52, v28
	v_readfirstlane_b32 s14, v44
	s_mov_b32 s15, m0
	s_mov_b32 m0, s14
	s_nop 0
	global_load_lds_dwordx4 v[38:39], off
	s_mov_b32 m0, s15
	v_lshl_add_u64 v[42:43], v[40:41], 0, s[30:31]
	v_readfirstlane_b32 s15, v45
	s_mov_b32 s39, m0
	s_mov_b32 m0, s15
	s_nop 0
	global_load_lds_dwordx4 v[42:43], off
	s_mov_b32 m0, s39
	v_lshl_add_u64 v[36:37], v[36:37], 0, s[34:35]
	s_addk_i32 s14, 0x1000
	s_mov_b32 s39, m0
	s_mov_b32 m0, s14
	s_nop 0
	global_load_lds_dwordx4 v[36:37], off
	s_mov_b32 m0, s39
	v_lshl_add_u64 v[36:37], v[40:41], 0, s[36:37]
	s_add_i32 s14, s15, 0x1000
	s_mov_b32 s15, m0
	s_mov_b32 m0, s14
	s_nop 0
	global_load_lds_dwordx4 v[36:37], off
	s_mov_b32 m0, s15
	s_branch .LBB0_1138

; #define VLOOP(t, N) for (int t##0_ = 2 * bid, t = min(t##0_ + vb, (N) - 1); t##0_ < (N); t##0_ += VG, t = min(t##0_ + vb, (N) - 1))
; __global__ void __launch_bounds__(512) hymba_fwd(Params p) {
;     ...
;         VLOOP(t, 8 * 32) { const int mt = t & 7, nt = t >> 3;
;             EpiResidBS e{x1 + (size_t)(TP + mt * 64) * LDB + nt * 64, x2 + (size_t)(TP + mt * 64) * LDB + nt * 64, LDB};
;             gemm_tile<32>(ctx + (size_t)(TP + mt * 64) * LDB, LDB, Wt_co + (size_t)nt * 64 * LDB, LDB, D, vlds, e);
.LBB0_1470:
	s_movk_i32 s96, 0x7f
	s_cmpk_eq_i32 s33, 0x100
	s_cselect_b32 s96, 0xff, s96
	s_cmp_gt_i32 s2, s96
	s_cbranch_scc1 .LBB0_1487
	s_ashr_i32 s42, s16, 8
	s_lshl_b32 s44, s2, 1
	s_lshl_b32 s43, s42, 16
	s_add_i32 s4, s42, s44
	s_min_i32 s38, s4, 0xff
	s_mov_b32 s96, 32
	s_mov_b32 s97, 29
	s_mov_b32 s98, 28
	s_mov_b32 s99, 0
	s_cmpk_lg_i32 s33, 0x100
	s_cbranch_scc1 .Lsk11_hdr
	s_mov_b32 s38, s2
	s_mov_b32 s96, 16
	s_mov_b32 s97, 13
	s_mov_b32 s98, 12
	s_lshl_b32 s99, s42, 11
.Lsk11_hdr:
	v_and_b32_e32 v1, 0xff, v0
	s_or_b32 s45, s43, 0x4000
	s_or_b32 s46, s43, 0x8000
	s_mov_b32 s5, 0
	v_mov_b32_e32 v24, 0x42000
	s_movk_i32 s47, 0x1080
	v_mov_b32_e32 v19, 0
	s_mov_b64 s[6:7], 0x21000
	s_mov_b64 s[8:9], 0x80
	s_mov_b64 s[10:11], 0x21080
	s_mov_b64 s[12:13], 0x100
	s_mov_b64 s[16:17], 0x21100
	s_mov_b32 s48, 0x1ffffe0
	s_mov_b64 s[18:19], 0x24139180
	s_mov_b64 s[20:21], 0x29c8180
	s_mov_b64 s[22:23], 0x2415a180
	s_mov_b64 s[24:25], 0x29e9180
	s_mov_b64 s[26:27], 0x24139200
	s_mov_b64 s[30:31], 0x29c8200
	s_mov_b64 s[34:35], 0x2415a200
	s_mov_b64 s[36:37], 0x29e9200
	s_branch .LBB0_1473

; #define LAS __attribute__((address_space(3)))
; #define GLDS_STAGE(st, kt_) do { \
;         _Pragma("unroll") for (int i_ = 0; i_ < FI; ++i_) { \
;             glds16(ap + (size_t)(32 * i_) * lda + (kt_) * 64, l3a + (st) + tid * 16 + i_ * 4096); \
;             glds16(bp + (size_t)(32 * i_) * ldb + (kt_) * 64, l3a + (st) + OPB + tid * 16 + i_ * 4096); } } while (0)
; #define GLDS_STAGE(st, kt_) do { \
;         _Pragma("unroll") for (int i_ = 0; i_ < 4; ++i_) { \
;             glds16(ap + (size_t)(64 * i_) * lda + (kt_) * 64, l3a + (st) + tid * 16 + i_ * 8192); \
;             glds16(bp + (size_t)(64 * i_) * ldb + (kt_) * 64, l3a + (st) + 32768 + tid * 16 + i_ * 8192); } } while (0)
; template <int WT, class Epi>
; DEV void gemm_tile(const bf16_t* __restrict__ A, int lda, const bf16_t* __restrict__ Bt, int ldb, int K, unsigned char* lds, const Epi& epi) {
;     ...
;     const int lrow = tid >> 3, lcs = (tid & 7) ^ (lrow & 7);
;     const bf16_t* ap = A + (size_t)lrow * lda + lcs * 8;
;     const bf16_t* bp = Bt + (size_t)lrow * ldb + lcs * 8;
;     const unsigned l3a = (unsigned)(size_t)(LAS unsigned char*)lds;
;     const int nk = K >> 6;
;     ...
;     constexpr int NSTG = 65536 / STB;
; #pragma unroll
;     for (int s_ = 0; s_ < NSTG - 1; ++s_) if (s_ < nk) GLDS_STAGE(s_ * STB, s_);
;     const int aoff = (wr * WT + fr) * 128, boff = OPB + (wc * WT + fr) * 128, sw = fr & 7;
.LBB0_1473:
	s_lshl_b32 s4, s38, 6
	s_and_b32 s4, s4, 0x1c0
	s_mulk_i32 s4, 0x840
	v_mov_b32_e32 v25, v1
	s_add_i32 s50, s4, 0x1080000
	s_lshl_b32 s4, s50, 1
	v_ashrrev_i32_e32 v13, 3, v25
	v_xor_b32_e32 v8, v13, v25
	s_ashr_i32 s49, s38, 3
	v_lshl_add_u64 v[2:3], v[132:133], 0, s[4:5]
	v_lshlrev_b32_e32 v8, 4, v8
	v_lshlrev_b32_e32 v27, 4, v25
	v_mad_i64_i32 v[4:5], s[40:41], s49, v24, v[160:161]
	v_mad_i64_i32 v[2:3], s[40:41], v13, s47, v[2:3]
	v_and_b32_e32 v18, 0x70, v8
	v_add_u32_e32 v18, s99, v18
	v_add_u32_e32 v28, 0x2000, v27
	v_add_u32_e32 v8, s43, v27
	v_lshl_add_u64 v[2:3], v[2:3], 0, v[18:19]
	v_mad_i64_i32 v[4:5], s[40:41], v13, s47, v[4:5]
	v_add_u32_e32 v9, s43, v28
	v_readfirstlane_b32 s4, v8
	s_mov_b32 s14, m0
	s_mov_b32 m0, s4
	s_nop 0
	global_load_lds_dwordx4 v[2:3], off
	s_mov_b32 m0, s14
	v_lshl_add_u64 v[4:5], v[4:5], 0, v[18:19]
	v_readfirstlane_b32 s14, v9
	s_mov_b32 s15, m0
	s_mov_b32 m0, s14
	s_nop 0
	global_load_lds_dwordx4 v[4:5], off
	s_mov_b32 m0, s15
	v_lshl_add_u64 v[8:9], v[2:3], 0, s[6:7]
	s_addk_i32 s4, 0x1000
	s_mov_b32 s15, m0
	s_mov_b32 m0, s4
	s_nop 0
	global_load_lds_dwordx4 v[8:9], off
	s_mov_b32 m0, s15
	v_lshl_add_u64 v[8:9], v[4:5], 0, s[6:7]
	s_add_i32 s4, s14, 0x1000
	s_mov_b32 s14, m0
	s_mov_b32 m0, s4
	s_nop 0
	global_load_lds_dwordx4 v[8:9], off
	s_mov_b32 m0, s14
	v_add_u32_e32 v14, s45, v27
	v_lshl_add_u64 v[8:9], v[2:3], 0, s[8:9]
	v_add_u32_e32 v15, s45, v28
	v_readfirstlane_b32 s4, v14
	s_mov_b32 s14, m0
	s_mov_b32 m0, s4
	s_nop 0
	global_load_lds_dwordx4 v[8:9], off
	s_mov_b32 m0, s14
	v_lshl_add_u64 v[10:11], v[4:5], 0, s[8:9]
	v_readfirstlane_b32 s14, v15
	s_mov_b32 s15, m0
	s_mov_b32 m0, s14
	s_nop 0
	global_load_lds_dwordx4 v[10:11], off
	s_mov_b32 m0, s15
	v_lshl_add_u64 v[8:9], v[2:3], 0, s[10:11]
	s_addk_i32 s4, 0x1000
	s_mov_b32 s15, m0
	s_mov_b32 m0, s4
	s_nop 0
	global_load_lds_dwordx4 v[8:9], off
	s_mov_b32 m0, s15
	v_lshl_add_u64 v[8:9], v[4:5], 0, s[10:11]
	s_add_i32 s4, s14, 0x1000
	s_mov_b32 s14, m0
	s_mov_b32 m0, s4
	s_nop 0
	global_load_lds_dwordx4 v[8:9], off
	s_mov_b32 m0, s14
	v_add_u32_e32 v14, s46, v27
	v_lshl_add_u64 v[8:9], v[2:3], 0, s[12:13]
	v_add_u32_e32 v15, s46, v28
	v_readfirstlane_b32 s4, v14
	s_mov_b32 s14, m0
	s_mov_b32 m0, s4
	s_nop 0
	global_load_lds_dwordx4 v[8:9], off
	s_mov_b32 m0, s14
	v_lshl_add_u64 v[10:11], v[4:5], 0, s[12:13]
	v_readfirstlane_b32 s14, v15
	s_mov_b32 s15, m0
	s_mov_b32 m0, s14
	s_nop 0
	global_load_lds_dwordx4 v[10:11], off
	s_mov_b32 m0, s15
	v_lshl_add_u64 v[2:3], v[2:3], 0, s[16:17]
	s_addk_i32 s4, 0x1000
	s_mov_b32 s15, m0
	s_mov_b32 m0, s4
	s_nop 0
	global_load_lds_dwordx4 v[2:3], off
	s_mov_b32 m0, s15
	v_lshl_add_u64 v[2:3], v[4:5], 0, s[16:17]
	v_and_b32_e32 v12, 15, v25
	s_add_i32 s4, s14, 0x1000
	s_mov_b32 s14, m0
	s_mov_b32 m0, s4
	s_nop 0
	global_load_lds_dwordx4 v[2:3], off
	s_mov_b32 m0, s14
	v_lshrrev_b32_e32 v2, 2, v25
	v_and_or_b32 v2, v2, s48, v12
	v_lshlrev_b32_e32 v31, 7, v2
	v_lshrrev_b32_e32 v2, 1, v25
	v_and_b32_e32 v32, 32, v2
	v_lshrrev_b32_e32 v26, 4, v25
	v_or_b32_e32 v2, v32, v12
	v_and_b32_e32 v29, 7, v25
	v_bfe_u32 v30, v25, 4, 2
	v_lshlrev_b32_e32 v33, 7, v2
	v_bitop3_b32 v2, v26, v29, 3 bitop3:0x6c
	v_lshlrev_b32_e32 v34, 4, v2
	v_bitop3_b32 v2, v30, v29, 4 bitop3:0x36
	v_mad_i64_i32 v[6:7], s[40:41], v13, s47, 0
	v_lshlrev_b32_e32 v35, 4, v2
	v_bitop3_b32 v2, v13, 7, v25 bitop3:0x48
	v_lshlrev_b32_e32 v18, 4, v2
	v_add_u32_e32 v18, s99, v18
	v_mad_i64_i32 v[2:3], s[40:41], s49, v24, v[6:7]
	s_and_b32 s4, s38, 7
	v_lshl_add_u64 v[20:21], v[158:159], 0, v[2:3]
	v_mad_u64_u32 v[2:3], s[38:39], s4, v24, v[6:7]
	v_lshl_add_u64 v[22:23], v[158:159], 0, v[2:3]
	s_mov_b32 s52, 0xc000
	s_mov_b32 s4, 0
	s_mov_b32 s51, 0
	v_mov_b32_e32 v6, v19
	v_mov_b32_e32 v7, v19
	v_mov_b32_e32 v8, v19
	v_mov_b32_e32 v9, v19
	v_mov_b32_e32 v2, v19
	v_mov_b32_e32 v3, v19
	v_mov_b32_e32 v4, v19
	v_mov_b32_e32 v5, v19
	v_mov_b32_e32 v10, v19
	v_mov_b32_e32 v11, v19
	v_mov_b32_e32 v12, v19
	v_mov_b32_e32 v13, v19
	v_mov_b32_e32 v14, v19
	v_mov_b32_e32 v15, v19
	v_mov_b32_e32 v16, v19
	v_mov_b32_e32 v17, v19
	s_branch .LBB0_1475

; __global__ void __launch_bounds__(512) hymba_fwd(Params p) {
;     __shared__ __attribute__((aligned(16))) unsigned char lds[131072];
	.amdhsa_kernel _Z9hymba_fwd6Params
		.amdhsa_group_segment_fixed_size 131088
		.amdhsa_private_segment_fixed_size 0
		.amdhsa_kernarg_size 472
		.amdhsa_user_sgpr_count 2
		.amdhsa_user_sgpr_dispatch_ptr 0
		.amdhsa_user_sgpr_queue_ptr 0
		.amdhsa_user_sgpr_kernarg_segment_ptr 1
		.amdhsa_user_sgpr_dispatch_id 0
		.amdhsa_user_sgpr_kernarg_preload_length 0
		.amdhsa_user_sgpr_kernarg_preload_offset 0
		.amdhsa_user_sgpr_private_segment_size 0
		.amdhsa_uses_dynamic_stack 0
		.amdhsa_enable_private_segment 0
		.amdhsa_system_sgpr_workgroup_id_x 1
		.amdhsa_system_sgpr_workgroup_id_y 0
		.amdhsa_system_sgpr_workgroup_id_z 0
		.amdhsa_system_sgpr_workgroup_info 0
		.amdhsa_system_vgpr_workitem_id 0
		.amdhsa_next_free_vgpr 253
		.amdhsa_next_free_sgpr 100
		.amdhsa_accum_offset 256
		.amdhsa_reserve_vcc 1
		.amdhsa_float_round_mode_32 0
		.amdhsa_float_round_mode_16_64 0
		.amdhsa_float_denorm_mode_32 3
		.amdhsa_float_denorm_mode_16_64 3
		.amdhsa_dx10_clamp 1
		.amdhsa_ieee_mode 1
		.amdhsa_fp16_overflow 0
		.amdhsa_tg_split 0
		.amdhsa_exception_fp_ieee_invalid_op 0
		.amdhsa_exception_fp_denorm_src 0
		.amdhsa_exception_fp_ieee_div_zero 0
		.amdhsa_exception_fp_ieee_overflow 0
		.amdhsa_exception_fp_ieee_underflow 0
		.amdhsa_exception_fp_ieee_inexact 0
		.amdhsa_exception_int_div_zero 0
	.end_amdhsa_kernel

; __global__ void __launch_bounds__(512) hymba_fwd(Params p) {
;     __shared__ __attribute__((aligned(16))) unsigned char lds[131072];
amdhsa.kernels:
  - .agpr_count:     0
    .args:
      - .offset:         0
        .size:           216
        .value_kind:     by_value
      - .offset:         216
        .size:           4
        .value_kind:     hidden_block_count_x
      - .offset:         220
        .size:           4
        .value_kind:     hidden_block_count_y
      - .offset:         224
        .size:           4
        .value_kind:     hidden_block_count_z
      - .offset:         228
        .size:           2
        .value_kind:     hidden_group_size_x
      - .offset:         230
        .size:           2
        .value_kind:     hidden_group_size_y
      - .offset:         232
        .size:           2
        .value_kind:     hidden_group_size_z
      - .offset:         234
        .size:           2
        .value_kind:     hidden_remainder_x
      - .offset:         236
        .size:           2
        .value_kind:     hidden_remainder_y
      - .offset:         238
        .size:           2
        .value_kind:     hidden_remainder_z
      - .offset:         256
        .size:           8
        .value_kind:     hidden_global_offset_x
      - .offset:         264
        .size:           8
        .value_kind:     hidden_global_offset_y
      - .offset:         272
        .size:           8
        .value_kind:     hidden_global_offset_z
      - .offset:         280
        .size:           2
        .value_kind:     hidden_grid_dims
    .group_segment_fixed_size: 131088
    .kernarg_segment_align: 8
    .kernarg_segment_size: 472
    .language:       OpenCL C
    .language_version:
      - 2
      - 0
    .max_flat_workgroup_size: 512
    .name:           _Z9hymba_fwd6Params
    .private_segment_fixed_size: 0
    .sgpr_count:     106
    .sgpr_spill_count: 4
    .symbol:         _Z9hymba_fwd6Params.kd
    .uniform_work_group_size: 1
    .uses_dynamic_stack: false
    .vgpr_count:     253
    .vgpr_spill_count: 0
    .wavefront_size: 64
